# EpiUp regenerated by hand over pairs of adjacent channels with packed f32 ops (v_pk_fma/mul/add): 9 instead of 14 instructions per element, same f32 arithmetic (fused mul-adds)
# speedup vs baseline: 1.1069x; 1.0169x over previous
.LBB0_782:
	v_lshl_or_b32 v184, s44, 7, v192
	v_ashrrev_i32_e32 v185, 31, v184
	v_lshlrev_b64 v[116:117], 2, v[184:185]
	v_lshl_add_u64 v[182:183], s[0:1], 0, v[116:117]
	v_lshl_add_u64 v[180:181], s[12:13], 0, v[116:117]
	v_lshl_add_u64 v[178:179], s[14:15], 0, v[116:117]
	v_lshl_add_u64 v[176:177], s[2:3], 0, v[116:117]
	global_load_dwordx4 v[140:143], v[182:183], off offset:16
	global_load_dwordx4 v[156:159], v[182:183], off
	global_load_dwordx4 v[116:119], v[180:181], off offset:16
	global_load_dwordx4 v[144:147], v[180:181], off
	global_load_dwordx4 v[120:123], v[178:179], off offset:16
	global_load_dwordx4 v[148:151], v[178:179], off
	global_load_dwordx4 v[124:127], v[176:177], off offset:16
	global_load_dwordx4 v[152:155], v[176:177], off
	v_lshl_add_u32 v194, s45, 8, v190
	s_movk_i32 s17, 0xb00
	v_readlane_b32 s24, v253, 0
	v_readlane_b32 s25, v253, 1
	v_readlane_b32 s26, v253, 2
	v_readlane_b32 s27, v253, 3
	s_andn2_b64 vcc, exec, s[6:7]
	v_mul_lo_u32 v194, v194, s17
	v_mov_b32_e32 v188, 0xbfb8aa3b
	v_mov_b32_e32 v189, 0xbfb8aa3b
	v_add_lshl_u32 v194, v194, v184, 1
	s_waitcnt vmcnt(0)
	v_mov_b32_dpp v172, v136 row_ror:1 row_mask:0xf bank_mask:0xf
	v_mov_b32_dpp v176, v132 row_ror:1 row_mask:0xf bank_mask:0xf
	v_mov_b32_dpp v178, v112 row_ror:1 row_mask:0xf bank_mask:0xf
	v_mov_b32_dpp v180, v132 row_ror:15 row_mask:0xf bank_mask:0xf
	v_mov_b32_dpp v182, v112 row_ror:15 row_mask:0xf bank_mask:0xf
	v_mov_b32_dpp v184, v104 row_ror:15 row_mask:0xf bank_mask:0xf
	v_mov_b32_dpp v173, v137 row_ror:1 row_mask:0xf bank_mask:0xf
	v_mov_b32_dpp v177, v133 row_ror:1 row_mask:0xf bank_mask:0xf
	v_mov_b32_dpp v179, v113 row_ror:1 row_mask:0xf bank_mask:0xf
	v_mov_b32_dpp v181, v133 row_ror:15 row_mask:0xf bank_mask:0xf
	v_mov_b32_dpp v183, v113 row_ror:15 row_mask:0xf bank_mask:0xf
	v_mov_b32_dpp v185, v105 row_ror:15 row_mask:0xf bank_mask:0xf
	v_mov_b32_dpp v170, v136 row_shr:1 row_mask:0xf bank_mask:0xf bound_ctrl:1
	v_mov_b32_dpp v172, v132 row_shr:1 row_mask:0xf bank_mask:0xf
	v_mov_b32_dpp v176, v112 row_shr:1 row_mask:0xf bank_mask:0xf
	v_mov_b32_dpp v178, v104 row_shr:1 row_mask:0xf bank_mask:0xf
	v_mov_b32_dpp v180, v136 row_shl:1 row_mask:0xf bank_mask:0xf
	v_mov_b32_dpp v182, v132 row_shl:1 row_mask:0xf bank_mask:0xf
	v_mov_b32_dpp v184, v112 row_shl:1 row_mask:0xf bank_mask:0xf
	v_mov_b32_dpp v186, v104 row_shl:1 row_mask:0xf bank_mask:0xf bound_ctrl:1
	v_mov_b32_dpp v171, v137 row_shr:1 row_mask:0xf bank_mask:0xf bound_ctrl:1
	v_mov_b32_dpp v173, v133 row_shr:1 row_mask:0xf bank_mask:0xf
	v_mov_b32_dpp v177, v113 row_shr:1 row_mask:0xf bank_mask:0xf
	v_mov_b32_dpp v179, v105 row_shr:1 row_mask:0xf bank_mask:0xf
	v_mov_b32_dpp v181, v137 row_shl:1 row_mask:0xf bank_mask:0xf
	v_mov_b32_dpp v183, v133 row_shl:1 row_mask:0xf bank_mask:0xf
	v_mov_b32_dpp v185, v113 row_shl:1 row_mask:0xf bank_mask:0xf
	v_mov_b32_dpp v187, v105 row_shl:1 row_mask:0xf bank_mask:0xf bound_ctrl:1
	v_pk_fma_f32 v[170:171], v[170:171], v[156:157], v[152:153]
	v_pk_fma_f32 v[172:173], v[172:173], v[156:157], v[152:153]
	v_pk_fma_f32 v[176:177], v[176:177], v[156:157], v[152:153]
	v_pk_fma_f32 v[178:179], v[178:179], v[156:157], v[152:153]
	v_pk_fma_f32 v[170:171], v[136:137], v[144:145], v[170:171]
	v_pk_fma_f32 v[172:173], v[132:133], v[144:145], v[172:173]
	v_pk_fma_f32 v[176:177], v[112:113], v[144:145], v[176:177]
	v_pk_fma_f32 v[178:179], v[104:105], v[144:145], v[178:179]
	v_pk_fma_f32 v[170:171], v[180:181], v[148:149], v[170:171]
	v_pk_fma_f32 v[172:173], v[182:183], v[148:149], v[172:173]
	v_pk_fma_f32 v[176:177], v[184:185], v[148:149], v[176:177]
	v_pk_fma_f32 v[178:179], v[186:187], v[148:149], v[178:179]
	v_pk_mul_f32 v[180:181], v[170:171], v[188:189]
	v_pk_mul_f32 v[182:183], v[172:173], v[188:189]
	v_pk_mul_f32 v[184:185], v[176:177], v[188:189]
	v_pk_mul_f32 v[186:187], v[178:179], v[188:189]
	v_exp_f32_e32 v180, v180
	v_exp_f32_e32 v181, v181
	v_exp_f32_e32 v182, v182
	v_exp_f32_e32 v183, v183
	v_exp_f32_e32 v184, v184
	v_exp_f32_e32 v185, v185
	v_exp_f32_e32 v186, v186
	v_exp_f32_e32 v187, v187
	s_nop 0
	v_pk_add_f32 v[180:181], v[180:181], 1.0 op_sel_hi:[1,0]
	v_pk_add_f32 v[182:183], v[182:183], 1.0 op_sel_hi:[1,0]
	v_pk_add_f32 v[184:185], v[184:185], 1.0 op_sel_hi:[1,0]
	v_pk_add_f32 v[186:187], v[186:187], 1.0 op_sel_hi:[1,0]
	v_rcp_f32_e32 v180, v180
	v_rcp_f32_e32 v181, v181
	v_rcp_f32_e32 v182, v182
	v_rcp_f32_e32 v183, v183
	v_rcp_f32_e32 v184, v184
	v_rcp_f32_e32 v185, v185
	v_rcp_f32_e32 v186, v186
	v_rcp_f32_e32 v187, v187
	s_nop 0
	v_pk_mul_f32 v[136:137], v[170:171], v[180:181]
	v_pk_mul_f32 v[132:133], v[172:173], v[182:183]
	v_pk_mul_f32 v[112:113], v[176:177], v[184:185]
	v_pk_mul_f32 v[104:105], v[178:179], v[186:187]
	v_pk_mul_f32 v[136:137], v[136:137], v[128:129]
	v_pk_mul_f32 v[132:133], v[132:133], v[108:109]
	v_pk_mul_f32 v[112:113], v[112:113], v[100:101]
	v_pk_mul_f32 v[104:105], v[104:105], v[96:97]
	v_mov_b32_dpp v172, v138 row_ror:1 row_mask:0xf bank_mask:0xf
	v_mov_b32_dpp v176, v134 row_ror:1 row_mask:0xf bank_mask:0xf
	v_mov_b32_dpp v178, v114 row_ror:1 row_mask:0xf bank_mask:0xf
	v_mov_b32_dpp v180, v134 row_ror:15 row_mask:0xf bank_mask:0xf
	v_mov_b32_dpp v182, v114 row_ror:15 row_mask:0xf bank_mask:0xf
	v_mov_b32_dpp v184, v106 row_ror:15 row_mask:0xf bank_mask:0xf
	v_mov_b32_dpp v173, v139 row_ror:1 row_mask:0xf bank_mask:0xf
	v_mov_b32_dpp v177, v135 row_ror:1 row_mask:0xf bank_mask:0xf
	v_mov_b32_dpp v179, v115 row_ror:1 row_mask:0xf bank_mask:0xf
	v_mov_b32_dpp v181, v135 row_ror:15 row_mask:0xf bank_mask:0xf
	v_mov_b32_dpp v183, v115 row_ror:15 row_mask:0xf bank_mask:0xf
	v_mov_b32_dpp v185, v107 row_ror:15 row_mask:0xf bank_mask:0xf
	v_mov_b32_dpp v170, v138 row_shr:1 row_mask:0xf bank_mask:0xf bound_ctrl:1
	v_mov_b32_dpp v172, v134 row_shr:1 row_mask:0xf bank_mask:0xf
	v_mov_b32_dpp v176, v114 row_shr:1 row_mask:0xf bank_mask:0xf
	v_mov_b32_dpp v178, v106 row_shr:1 row_mask:0xf bank_mask:0xf
	v_mov_b32_dpp v180, v138 row_shl:1 row_mask:0xf bank_mask:0xf
	v_mov_b32_dpp v182, v134 row_shl:1 row_mask:0xf bank_mask:0xf
	v_mov_b32_dpp v184, v114 row_shl:1 row_mask:0xf bank_mask:0xf
	v_mov_b32_dpp v186, v106 row_shl:1 row_mask:0xf bank_mask:0xf bound_ctrl:1
	v_mov_b32_dpp v171, v139 row_shr:1 row_mask:0xf bank_mask:0xf bound_ctrl:1
	v_mov_b32_dpp v173, v135 row_shr:1 row_mask:0xf bank_mask:0xf
	v_mov_b32_dpp v177, v115 row_shr:1 row_mask:0xf bank_mask:0xf
	v_mov_b32_dpp v179, v107 row_shr:1 row_mask:0xf bank_mask:0xf
	v_mov_b32_dpp v181, v139 row_shl:1 row_mask:0xf bank_mask:0xf
	v_mov_b32_dpp v183, v135 row_shl:1 row_mask:0xf bank_mask:0xf
	v_mov_b32_dpp v185, v115 row_shl:1 row_mask:0xf bank_mask:0xf
	v_mov_b32_dpp v187, v107 row_shl:1 row_mask:0xf bank_mask:0xf bound_ctrl:1
	v_pk_fma_f32 v[170:171], v[170:171], v[158:159], v[154:155]
	v_pk_fma_f32 v[172:173], v[172:173], v[158:159], v[154:155]
	v_pk_fma_f32 v[176:177], v[176:177], v[158:159], v[154:155]
	v_pk_fma_f32 v[178:179], v[178:179], v[158:159], v[154:155]
	v_pk_fma_f32 v[170:171], v[138:139], v[146:147], v[170:171]
	v_pk_fma_f32 v[172:173], v[134:135], v[146:147], v[172:173]
	v_pk_fma_f32 v[176:177], v[114:115], v[146:147], v[176:177]
	v_pk_fma_f32 v[178:179], v[106:107], v[146:147], v[178:179]
	v_pk_fma_f32 v[170:171], v[180:181], v[150:151], v[170:171]
	v_pk_fma_f32 v[172:173], v[182:183], v[150:151], v[172:173]
	v_pk_fma_f32 v[176:177], v[184:185], v[150:151], v[176:177]
	v_pk_fma_f32 v[178:179], v[186:187], v[150:151], v[178:179]
	v_pk_mul_f32 v[180:181], v[170:171], v[188:189]
	v_pk_mul_f32 v[182:183], v[172:173], v[188:189]
	v_pk_mul_f32 v[184:185], v[176:177], v[188:189]
	v_pk_mul_f32 v[186:187], v[178:179], v[188:189]
	v_exp_f32_e32 v180, v180
	v_exp_f32_e32 v181, v181
	v_exp_f32_e32 v182, v182
	v_exp_f32_e32 v183, v183
	v_exp_f32_e32 v184, v184
	v_exp_f32_e32 v185, v185
	v_exp_f32_e32 v186, v186
	v_exp_f32_e32 v187, v187
	s_nop 0
	v_pk_add_f32 v[180:181], v[180:181], 1.0 op_sel_hi:[1,0]
	v_pk_add_f32 v[182:183], v[182:183], 1.0 op_sel_hi:[1,0]
	v_pk_add_f32 v[184:185], v[184:185], 1.0 op_sel_hi:[1,0]
	v_pk_add_f32 v[186:187], v[186:187], 1.0 op_sel_hi:[1,0]
	v_rcp_f32_e32 v180, v180
	v_rcp_f32_e32 v181, v181
	v_rcp_f32_e32 v182, v182
	v_rcp_f32_e32 v183, v183
	v_rcp_f32_e32 v184, v184
	v_rcp_f32_e32 v185, v185
	v_rcp_f32_e32 v186, v186
	v_rcp_f32_e32 v187, v187
	s_nop 0
	v_pk_mul_f32 v[138:139], v[170:171], v[180:181]
	v_pk_mul_f32 v[134:135], v[172:173], v[182:183]
	v_pk_mul_f32 v[114:115], v[176:177], v[184:185]
	v_pk_mul_f32 v[106:107], v[178:179], v[186:187]
	v_pk_mul_f32 v[138:139], v[138:139], v[130:131]
	v_pk_mul_f32 v[134:135], v[134:135], v[110:111]
	v_pk_mul_f32 v[114:115], v[114:115], v[102:103]
	v_pk_mul_f32 v[106:107], v[106:107], v[98:99]
	v_mov_b32_dpp v172, v92 row_ror:1 row_mask:0xf bank_mask:0xf
	v_mov_b32_dpp v176, v88 row_ror:1 row_mask:0xf bank_mask:0xf
	v_mov_b32_dpp v178, v80 row_ror:1 row_mask:0xf bank_mask:0xf
	v_mov_b32_dpp v180, v88 row_ror:15 row_mask:0xf bank_mask:0xf
	v_mov_b32_dpp v182, v80 row_ror:15 row_mask:0xf bank_mask:0xf
	v_mov_b32_dpp v184, v72 row_ror:15 row_mask:0xf bank_mask:0xf
	v_mov_b32_dpp v173, v93 row_ror:1 row_mask:0xf bank_mask:0xf
	v_mov_b32_dpp v177, v89 row_ror:1 row_mask:0xf bank_mask:0xf
	v_mov_b32_dpp v179, v81 row_ror:1 row_mask:0xf bank_mask:0xf
	v_mov_b32_dpp v181, v89 row_ror:15 row_mask:0xf bank_mask:0xf
	v_mov_b32_dpp v183, v81 row_ror:15 row_mask:0xf bank_mask:0xf
	v_mov_b32_dpp v185, v73 row_ror:15 row_mask:0xf bank_mask:0xf
	v_mov_b32_dpp v170, v92 row_shr:1 row_mask:0xf bank_mask:0xf bound_ctrl:1
	v_mov_b32_dpp v172, v88 row_shr:1 row_mask:0xf bank_mask:0xf
	v_mov_b32_dpp v176, v80 row_shr:1 row_mask:0xf bank_mask:0xf
	v_mov_b32_dpp v178, v72 row_shr:1 row_mask:0xf bank_mask:0xf
	v_mov_b32_dpp v180, v92 row_shl:1 row_mask:0xf bank_mask:0xf
	v_mov_b32_dpp v182, v88 row_shl:1 row_mask:0xf bank_mask:0xf
	v_mov_b32_dpp v184, v80 row_shl:1 row_mask:0xf bank_mask:0xf
	v_mov_b32_dpp v186, v72 row_shl:1 row_mask:0xf bank_mask:0xf bound_ctrl:1
	v_mov_b32_dpp v171, v93 row_shr:1 row_mask:0xf bank_mask:0xf bound_ctrl:1
	v_mov_b32_dpp v173, v89 row_shr:1 row_mask:0xf bank_mask:0xf
	v_mov_b32_dpp v177, v81 row_shr:1 row_mask:0xf bank_mask:0xf
	v_mov_b32_dpp v179, v73 row_shr:1 row_mask:0xf bank_mask:0xf
	v_mov_b32_dpp v181, v93 row_shl:1 row_mask:0xf bank_mask:0xf
	v_mov_b32_dpp v183, v89 row_shl:1 row_mask:0xf bank_mask:0xf
	v_mov_b32_dpp v185, v81 row_shl:1 row_mask:0xf bank_mask:0xf
	v_mov_b32_dpp v187, v73 row_shl:1 row_mask:0xf bank_mask:0xf bound_ctrl:1
	v_pk_fma_f32 v[170:171], v[170:171], v[140:141], v[124:125]
	v_pk_fma_f32 v[172:173], v[172:173], v[140:141], v[124:125]
	v_pk_fma_f32 v[176:177], v[176:177], v[140:141], v[124:125]
	v_pk_fma_f32 v[178:179], v[178:179], v[140:141], v[124:125]
	v_pk_fma_f32 v[170:171], v[92:93], v[116:117], v[170:171]
	v_pk_fma_f32 v[172:173], v[88:89], v[116:117], v[172:173]
	v_pk_fma_f32 v[176:177], v[80:81], v[116:117], v[176:177]
	v_pk_fma_f32 v[178:179], v[72:73], v[116:117], v[178:179]
	v_pk_fma_f32 v[170:171], v[180:181], v[120:121], v[170:171]
	v_pk_fma_f32 v[172:173], v[182:183], v[120:121], v[172:173]
	v_pk_fma_f32 v[176:177], v[184:185], v[120:121], v[176:177]
	v_pk_fma_f32 v[178:179], v[186:187], v[120:121], v[178:179]
	v_pk_mul_f32 v[180:181], v[170:171], v[188:189]
	v_pk_mul_f32 v[182:183], v[172:173], v[188:189]
	v_pk_mul_f32 v[184:185], v[176:177], v[188:189]
	v_pk_mul_f32 v[186:187], v[178:179], v[188:189]
	v_exp_f32_e32 v180, v180
	v_exp_f32_e32 v181, v181
	v_exp_f32_e32 v182, v182
	v_exp_f32_e32 v183, v183
	v_exp_f32_e32 v184, v184
	v_exp_f32_e32 v185, v185
	v_exp_f32_e32 v186, v186
	v_exp_f32_e32 v187, v187
	s_nop 0
	v_pk_add_f32 v[180:181], v[180:181], 1.0 op_sel_hi:[1,0]
	v_pk_add_f32 v[182:183], v[182:183], 1.0 op_sel_hi:[1,0]
	v_pk_add_f32 v[184:185], v[184:185], 1.0 op_sel_hi:[1,0]
	v_pk_add_f32 v[186:187], v[186:187], 1.0 op_sel_hi:[1,0]
	v_rcp_f32_e32 v180, v180
	v_rcp_f32_e32 v181, v181
	v_rcp_f32_e32 v182, v182
	v_rcp_f32_e32 v183, v183
	v_rcp_f32_e32 v184, v184
	v_rcp_f32_e32 v185, v185
	v_rcp_f32_e32 v186, v186
	v_rcp_f32_e32 v187, v187
	s_nop 0
	v_pk_mul_f32 v[92:93], v[170:171], v[180:181]
	v_pk_mul_f32 v[88:89], v[172:173], v[182:183]
	v_pk_mul_f32 v[80:81], v[176:177], v[184:185]
	v_pk_mul_f32 v[72:73], v[178:179], v[186:187]
	v_pk_mul_f32 v[92:93], v[92:93], v[84:85]
	v_pk_mul_f32 v[88:89], v[88:89], v[76:77]
	v_pk_mul_f32 v[80:81], v[80:81], v[68:69]
	v_pk_mul_f32 v[72:73], v[72:73], v[64:65]
	v_mov_b32_dpp v172, v94 row_ror:1 row_mask:0xf bank_mask:0xf
	v_mov_b32_dpp v176, v90 row_ror:1 row_mask:0xf bank_mask:0xf
	v_mov_b32_dpp v178, v82 row_ror:1 row_mask:0xf bank_mask:0xf
	v_mov_b32_dpp v180, v90 row_ror:15 row_mask:0xf bank_mask:0xf
	v_mov_b32_dpp v182, v82 row_ror:15 row_mask:0xf bank_mask:0xf
	v_mov_b32_dpp v184, v74 row_ror:15 row_mask:0xf bank_mask:0xf
	v_mov_b32_dpp v173, v95 row_ror:1 row_mask:0xf bank_mask:0xf
	v_mov_b32_dpp v177, v91 row_ror:1 row_mask:0xf bank_mask:0xf
	v_mov_b32_dpp v179, v83 row_ror:1 row_mask:0xf bank_mask:0xf
	v_mov_b32_dpp v181, v91 row_ror:15 row_mask:0xf bank_mask:0xf
	v_mov_b32_dpp v183, v83 row_ror:15 row_mask:0xf bank_mask:0xf
	v_mov_b32_dpp v185, v75 row_ror:15 row_mask:0xf bank_mask:0xf
	v_mov_b32_dpp v170, v94 row_shr:1 row_mask:0xf bank_mask:0xf bound_ctrl:1
	v_mov_b32_dpp v172, v90 row_shr:1 row_mask:0xf bank_mask:0xf
	v_mov_b32_dpp v176, v82 row_shr:1 row_mask:0xf bank_mask:0xf
	v_mov_b32_dpp v178, v74 row_shr:1 row_mask:0xf bank_mask:0xf
	v_mov_b32_dpp v180, v94 row_shl:1 row_mask:0xf bank_mask:0xf
	v_mov_b32_dpp v182, v90 row_shl:1 row_mask:0xf bank_mask:0xf
	v_mov_b32_dpp v184, v82 row_shl:1 row_mask:0xf bank_mask:0xf
	v_mov_b32_dpp v186, v74 row_shl:1 row_mask:0xf bank_mask:0xf bound_ctrl:1
	v_mov_b32_dpp v171, v95 row_shr:1 row_mask:0xf bank_mask:0xf bound_ctrl:1
	v_mov_b32_dpp v173, v91 row_shr:1 row_mask:0xf bank_mask:0xf
	v_mov_b32_dpp v177, v83 row_shr:1 row_mask:0xf bank_mask:0xf
	v_mov_b32_dpp v179, v75 row_shr:1 row_mask:0xf bank_mask:0xf
	v_mov_b32_dpp v181, v95 row_shl:1 row_mask:0xf bank_mask:0xf
	v_mov_b32_dpp v183, v91 row_shl:1 row_mask:0xf bank_mask:0xf
	v_mov_b32_dpp v185, v83 row_shl:1 row_mask:0xf bank_mask:0xf
	v_mov_b32_dpp v187, v75 row_shl:1 row_mask:0xf bank_mask:0xf bound_ctrl:1
	v_pk_fma_f32 v[170:171], v[170:171], v[142:143], v[126:127]
	v_pk_fma_f32 v[172:173], v[172:173], v[142:143], v[126:127]
	v_pk_fma_f32 v[176:177], v[176:177], v[142:143], v[126:127]
	v_pk_fma_f32 v[178:179], v[178:179], v[142:143], v[126:127]
	v_pk_fma_f32 v[170:171], v[94:95], v[118:119], v[170:171]
	v_pk_fma_f32 v[172:173], v[90:91], v[118:119], v[172:173]
	v_pk_fma_f32 v[176:177], v[82:83], v[118:119], v[176:177]
	v_pk_fma_f32 v[178:179], v[74:75], v[118:119], v[178:179]
	v_pk_fma_f32 v[170:171], v[180:181], v[122:123], v[170:171]
	v_pk_fma_f32 v[172:173], v[182:183], v[122:123], v[172:173]
	v_pk_fma_f32 v[176:177], v[184:185], v[122:123], v[176:177]
	v_pk_fma_f32 v[178:179], v[186:187], v[122:123], v[178:179]
	v_pk_mul_f32 v[180:181], v[170:171], v[188:189]
	v_pk_mul_f32 v[182:183], v[172:173], v[188:189]
	v_pk_mul_f32 v[184:185], v[176:177], v[188:189]
	v_pk_mul_f32 v[186:187], v[178:179], v[188:189]
	v_exp_f32_e32 v180, v180
	v_exp_f32_e32 v181, v181
	v_exp_f32_e32 v182, v182
	v_exp_f32_e32 v183, v183
	v_exp_f32_e32 v184, v184
	v_exp_f32_e32 v185, v185
	v_exp_f32_e32 v186, v186
	v_exp_f32_e32 v187, v187
	s_nop 0
	v_pk_add_f32 v[180:181], v[180:181], 1.0 op_sel_hi:[1,0]
	v_pk_add_f32 v[182:183], v[182:183], 1.0 op_sel_hi:[1,0]
	v_pk_add_f32 v[184:185], v[184:185], 1.0 op_sel_hi:[1,0]
	v_pk_add_f32 v[186:187], v[186:187], 1.0 op_sel_hi:[1,0]
	v_rcp_f32_e32 v180, v180
	v_rcp_f32_e32 v181, v181
	v_rcp_f32_e32 v182, v182
	v_rcp_f32_e32 v183, v183
	v_rcp_f32_e32 v184, v184
	v_rcp_f32_e32 v185, v185
	v_rcp_f32_e32 v186, v186
	v_rcp_f32_e32 v187, v187
	s_nop 0
	v_pk_mul_f32 v[94:95], v[170:171], v[180:181]
	v_pk_mul_f32 v[90:91], v[172:173], v[182:183]
	v_pk_mul_f32 v[82:83], v[176:177], v[184:185]
	v_pk_mul_f32 v[74:75], v[178:179], v[186:187]
	v_pk_mul_f32 v[94:95], v[94:95], v[86:87]
	v_pk_mul_f32 v[90:91], v[90:91], v[78:79]
	v_pk_mul_f32 v[82:83], v[82:83], v[70:71]
	v_pk_mul_f32 v[74:75], v[74:75], v[66:67]
	v_cvt_pk_bf16_f32 v128, v136, v137
	v_cvt_pk_bf16_f32 v129, v138, v139
	v_cvt_pk_bf16_f32 v130, v92, v93
	v_cvt_pk_bf16_f32 v131, v94, v95
	buffer_store_dwordx4 v[128:131], v194, s[24:27], 0 offen sc1
	v_cvt_pk_bf16_f32 v108, v132, v133
	v_cvt_pk_bf16_f32 v109, v134, v135
	v_cvt_pk_bf16_f32 v110, v88, v89
	v_cvt_pk_bf16_f32 v111, v90, v91
	v_add_u32_e32 v195, 0x16000, v194
	buffer_store_dwordx4 v[108:111], v195, s[24:27], 0 offen sc1
	v_cvt_pk_bf16_f32 v100, v112, v113
	v_cvt_pk_bf16_f32 v101, v114, v115
	v_cvt_pk_bf16_f32 v102, v80, v81
	v_cvt_pk_bf16_f32 v103, v82, v83
	v_add_u32_e32 v195, 0x2c000, v194
	buffer_store_dwordx4 v[100:103], v195, s[24:27], 0 offen sc1
	v_cvt_pk_bf16_f32 v96, v104, v105
	v_cvt_pk_bf16_f32 v97, v106, v107
	v_cvt_pk_bf16_f32 v98, v72, v73
	v_cvt_pk_bf16_f32 v99, v74, v75
	v_add_u32_e32 v195, 0x42000, v194
	buffer_store_dwordx4 v[96:99], v195, s[24:27], 0 offen sc1
	v_mov_b32_dpp v172, v60 row_ror:1 row_mask:0xf bank_mask:0xf
	v_mov_b32_dpp v176, v56 row_ror:1 row_mask:0xf bank_mask:0xf
	v_mov_b32_dpp v178, v48 row_ror:1 row_mask:0xf bank_mask:0xf
	v_mov_b32_dpp v180, v56 row_ror:15 row_mask:0xf bank_mask:0xf
	v_mov_b32_dpp v182, v48 row_ror:15 row_mask:0xf bank_mask:0xf
	v_mov_b32_dpp v184, v40 row_ror:15 row_mask:0xf bank_mask:0xf
	v_mov_b32_dpp v173, v61 row_ror:1 row_mask:0xf bank_mask:0xf
	v_mov_b32_dpp v177, v57 row_ror:1 row_mask:0xf bank_mask:0xf
	v_mov_b32_dpp v179, v49 row_ror:1 row_mask:0xf bank_mask:0xf
	v_mov_b32_dpp v181, v57 row_ror:15 row_mask:0xf bank_mask:0xf
	v_mov_b32_dpp v183, v49 row_ror:15 row_mask:0xf bank_mask:0xf
	v_mov_b32_dpp v185, v41 row_ror:15 row_mask:0xf bank_mask:0xf
	v_mov_b32_dpp v170, v60 row_shr:1 row_mask:0xf bank_mask:0xf bound_ctrl:1
	v_mov_b32_dpp v172, v56 row_shr:1 row_mask:0xf bank_mask:0xf
	v_mov_b32_dpp v176, v48 row_shr:1 row_mask:0xf bank_mask:0xf
	v_mov_b32_dpp v178, v40 row_shr:1 row_mask:0xf bank_mask:0xf
	v_mov_b32_dpp v180, v60 row_shl:1 row_mask:0xf bank_mask:0xf
	v_mov_b32_dpp v182, v56 row_shl:1 row_mask:0xf bank_mask:0xf
	v_mov_b32_dpp v184, v48 row_shl:1 row_mask:0xf bank_mask:0xf
	v_mov_b32_dpp v186, v40 row_shl:1 row_mask:0xf bank_mask:0xf bound_ctrl:1
	v_mov_b32_dpp v171, v61 row_shr:1 row_mask:0xf bank_mask:0xf bound_ctrl:1
	v_mov_b32_dpp v173, v57 row_shr:1 row_mask:0xf bank_mask:0xf
	v_mov_b32_dpp v177, v49 row_shr:1 row_mask:0xf bank_mask:0xf
	v_mov_b32_dpp v179, v41 row_shr:1 row_mask:0xf bank_mask:0xf
	v_mov_b32_dpp v181, v61 row_shl:1 row_mask:0xf bank_mask:0xf
	v_mov_b32_dpp v183, v57 row_shl:1 row_mask:0xf bank_mask:0xf
	v_mov_b32_dpp v185, v49 row_shl:1 row_mask:0xf bank_mask:0xf
	v_mov_b32_dpp v187, v41 row_shl:1 row_mask:0xf bank_mask:0xf bound_ctrl:1
	v_pk_fma_f32 v[170:171], v[170:171], v[156:157], v[152:153]
	v_pk_fma_f32 v[172:173], v[172:173], v[156:157], v[152:153]
	v_pk_fma_f32 v[176:177], v[176:177], v[156:157], v[152:153]
	v_pk_fma_f32 v[178:179], v[178:179], v[156:157], v[152:153]
	v_pk_fma_f32 v[170:171], v[60:61], v[144:145], v[170:171]
	v_pk_fma_f32 v[172:173], v[56:57], v[144:145], v[172:173]
	v_pk_fma_f32 v[176:177], v[48:49], v[144:145], v[176:177]
	v_pk_fma_f32 v[178:179], v[40:41], v[144:145], v[178:179]
	v_pk_fma_f32 v[170:171], v[180:181], v[148:149], v[170:171]
	v_pk_fma_f32 v[172:173], v[182:183], v[148:149], v[172:173]
	v_pk_fma_f32 v[176:177], v[184:185], v[148:149], v[176:177]
	v_pk_fma_f32 v[178:179], v[186:187], v[148:149], v[178:179]
	v_pk_mul_f32 v[180:181], v[170:171], v[188:189]
	v_pk_mul_f32 v[182:183], v[172:173], v[188:189]
	v_pk_mul_f32 v[184:185], v[176:177], v[188:189]
	v_pk_mul_f32 v[186:187], v[178:179], v[188:189]
	v_exp_f32_e32 v180, v180
	v_exp_f32_e32 v181, v181
	v_exp_f32_e32 v182, v182
	v_exp_f32_e32 v183, v183
	v_exp_f32_e32 v184, v184
	v_exp_f32_e32 v185, v185
	v_exp_f32_e32 v186, v186
	v_exp_f32_e32 v187, v187
	s_nop 0
	v_pk_add_f32 v[180:181], v[180:181], 1.0 op_sel_hi:[1,0]
	v_pk_add_f32 v[182:183], v[182:183], 1.0 op_sel_hi:[1,0]
	v_pk_add_f32 v[184:185], v[184:185], 1.0 op_sel_hi:[1,0]
	v_pk_add_f32 v[186:187], v[186:187], 1.0 op_sel_hi:[1,0]
	v_rcp_f32_e32 v180, v180
	v_rcp_f32_e32 v181, v181
	v_rcp_f32_e32 v182, v182
	v_rcp_f32_e32 v183, v183
	v_rcp_f32_e32 v184, v184
	v_rcp_f32_e32 v185, v185
	v_rcp_f32_e32 v186, v186
	v_rcp_f32_e32 v187, v187
	s_nop 0
	v_pk_mul_f32 v[60:61], v[170:171], v[180:181]
	v_pk_mul_f32 v[56:57], v[172:173], v[182:183]
	v_pk_mul_f32 v[48:49], v[176:177], v[184:185]
	v_pk_mul_f32 v[40:41], v[178:179], v[186:187]
	v_pk_mul_f32 v[60:61], v[60:61], v[52:53]
	v_pk_mul_f32 v[56:57], v[56:57], v[44:45]
	v_pk_mul_f32 v[48:49], v[48:49], v[36:37]
	v_pk_mul_f32 v[40:41], v[40:41], v[32:33]
	v_mov_b32_dpp v172, v62 row_ror:1 row_mask:0xf bank_mask:0xf
	v_mov_b32_dpp v176, v58 row_ror:1 row_mask:0xf bank_mask:0xf
	v_mov_b32_dpp v178, v50 row_ror:1 row_mask:0xf bank_mask:0xf
	v_mov_b32_dpp v180, v58 row_ror:15 row_mask:0xf bank_mask:0xf
	v_mov_b32_dpp v182, v50 row_ror:15 row_mask:0xf bank_mask:0xf
	v_mov_b32_dpp v184, v42 row_ror:15 row_mask:0xf bank_mask:0xf
	v_mov_b32_dpp v173, v63 row_ror:1 row_mask:0xf bank_mask:0xf
	v_mov_b32_dpp v177, v59 row_ror:1 row_mask:0xf bank_mask:0xf
	v_mov_b32_dpp v179, v51 row_ror:1 row_mask:0xf bank_mask:0xf
	v_mov_b32_dpp v181, v59 row_ror:15 row_mask:0xf bank_mask:0xf
	v_mov_b32_dpp v183, v51 row_ror:15 row_mask:0xf bank_mask:0xf
	v_mov_b32_dpp v185, v43 row_ror:15 row_mask:0xf bank_mask:0xf
	v_mov_b32_dpp v170, v62 row_shr:1 row_mask:0xf bank_mask:0xf bound_ctrl:1
	v_mov_b32_dpp v172, v58 row_shr:1 row_mask:0xf bank_mask:0xf
	v_mov_b32_dpp v176, v50 row_shr:1 row_mask:0xf bank_mask:0xf
	v_mov_b32_dpp v178, v42 row_shr:1 row_mask:0xf bank_mask:0xf
	v_mov_b32_dpp v180, v62 row_shl:1 row_mask:0xf bank_mask:0xf
	v_mov_b32_dpp v182, v58 row_shl:1 row_mask:0xf bank_mask:0xf
	v_mov_b32_dpp v184, v50 row_shl:1 row_mask:0xf bank_mask:0xf
	v_mov_b32_dpp v186, v42 row_shl:1 row_mask:0xf bank_mask:0xf bound_ctrl:1
	v_mov_b32_dpp v171, v63 row_shr:1 row_mask:0xf bank_mask:0xf bound_ctrl:1
	v_mov_b32_dpp v173, v59 row_shr:1 row_mask:0xf bank_mask:0xf
	v_mov_b32_dpp v177, v51 row_shr:1 row_mask:0xf bank_mask:0xf
	v_mov_b32_dpp v179, v43 row_shr:1 row_mask:0xf bank_mask:0xf
	v_mov_b32_dpp v181, v63 row_shl:1 row_mask:0xf bank_mask:0xf
	v_mov_b32_dpp v183, v59 row_shl:1 row_mask:0xf bank_mask:0xf
	v_mov_b32_dpp v185, v51 row_shl:1 row_mask:0xf bank_mask:0xf
	v_mov_b32_dpp v187, v43 row_shl:1 row_mask:0xf bank_mask:0xf bound_ctrl:1
	v_pk_fma_f32 v[170:171], v[170:171], v[158:159], v[154:155]
	v_pk_fma_f32 v[172:173], v[172:173], v[158:159], v[154:155]
	v_pk_fma_f32 v[176:177], v[176:177], v[158:159], v[154:155]
	v_pk_fma_f32 v[178:179], v[178:179], v[158:159], v[154:155]
	v_pk_fma_f32 v[170:171], v[62:63], v[146:147], v[170:171]
	v_pk_fma_f32 v[172:173], v[58:59], v[146:147], v[172:173]
	v_pk_fma_f32 v[176:177], v[50:51], v[146:147], v[176:177]
	v_pk_fma_f32 v[178:179], v[42:43], v[146:147], v[178:179]
	v_pk_fma_f32 v[170:171], v[180:181], v[150:151], v[170:171]
	v_pk_fma_f32 v[172:173], v[182:183], v[150:151], v[172:173]
	v_pk_fma_f32 v[176:177], v[184:185], v[150:151], v[176:177]
	v_pk_fma_f32 v[178:179], v[186:187], v[150:151], v[178:179]
	v_pk_mul_f32 v[180:181], v[170:171], v[188:189]
	v_pk_mul_f32 v[182:183], v[172:173], v[188:189]
	v_pk_mul_f32 v[184:185], v[176:177], v[188:189]
	v_pk_mul_f32 v[186:187], v[178:179], v[188:189]
	v_exp_f32_e32 v180, v180
	v_exp_f32_e32 v181, v181
	v_exp_f32_e32 v182, v182
	v_exp_f32_e32 v183, v183
	v_exp_f32_e32 v184, v184
	v_exp_f32_e32 v185, v185
	v_exp_f32_e32 v186, v186
	v_exp_f32_e32 v187, v187
	s_nop 0
	v_pk_add_f32 v[180:181], v[180:181], 1.0 op_sel_hi:[1,0]
	v_pk_add_f32 v[182:183], v[182:183], 1.0 op_sel_hi:[1,0]
	v_pk_add_f32 v[184:185], v[184:185], 1.0 op_sel_hi:[1,0]
	v_pk_add_f32 v[186:187], v[186:187], 1.0 op_sel_hi:[1,0]
	v_rcp_f32_e32 v180, v180
	v_rcp_f32_e32 v181, v181
	v_rcp_f32_e32 v182, v182
	v_rcp_f32_e32 v183, v183
	v_rcp_f32_e32 v184, v184
	v_rcp_f32_e32 v185, v185
	v_rcp_f32_e32 v186, v186
	v_rcp_f32_e32 v187, v187
	s_nop 0
	v_pk_mul_f32 v[62:63], v[170:171], v[180:181]
	v_pk_mul_f32 v[58:59], v[172:173], v[182:183]
	v_pk_mul_f32 v[50:51], v[176:177], v[184:185]
	v_pk_mul_f32 v[42:43], v[178:179], v[186:187]
	v_pk_mul_f32 v[62:63], v[62:63], v[54:55]
	v_pk_mul_f32 v[58:59], v[58:59], v[46:47]
	v_pk_mul_f32 v[50:51], v[50:51], v[38:39]
	v_pk_mul_f32 v[42:43], v[42:43], v[34:35]
	v_mov_b32_dpp v172, v28 row_ror:1 row_mask:0xf bank_mask:0xf
	v_mov_b32_dpp v176, v24 row_ror:1 row_mask:0xf bank_mask:0xf
	v_mov_b32_dpp v178, v16 row_ror:1 row_mask:0xf bank_mask:0xf
	v_mov_b32_dpp v180, v24 row_ror:15 row_mask:0xf bank_mask:0xf
	v_mov_b32_dpp v182, v16 row_ror:15 row_mask:0xf bank_mask:0xf
	v_mov_b32_dpp v184, v8 row_ror:15 row_mask:0xf bank_mask:0xf
	v_mov_b32_dpp v173, v29 row_ror:1 row_mask:0xf bank_mask:0xf
	v_mov_b32_dpp v177, v25 row_ror:1 row_mask:0xf bank_mask:0xf
	v_mov_b32_dpp v179, v17 row_ror:1 row_mask:0xf bank_mask:0xf
	v_mov_b32_dpp v181, v25 row_ror:15 row_mask:0xf bank_mask:0xf
	v_mov_b32_dpp v183, v17 row_ror:15 row_mask:0xf bank_mask:0xf
	v_mov_b32_dpp v185, v9 row_ror:15 row_mask:0xf bank_mask:0xf
	v_mov_b32_dpp v170, v28 row_shr:1 row_mask:0xf bank_mask:0xf bound_ctrl:1
	v_mov_b32_dpp v172, v24 row_shr:1 row_mask:0xf bank_mask:0xf
	v_mov_b32_dpp v176, v16 row_shr:1 row_mask:0xf bank_mask:0xf
	v_mov_b32_dpp v178, v8 row_shr:1 row_mask:0xf bank_mask:0xf
	v_mov_b32_dpp v180, v28 row_shl:1 row_mask:0xf bank_mask:0xf
	v_mov_b32_dpp v182, v24 row_shl:1 row_mask:0xf bank_mask:0xf
	v_mov_b32_dpp v184, v16 row_shl:1 row_mask:0xf bank_mask:0xf
	v_mov_b32_dpp v186, v8 row_shl:1 row_mask:0xf bank_mask:0xf bound_ctrl:1
	v_mov_b32_dpp v171, v29 row_shr:1 row_mask:0xf bank_mask:0xf bound_ctrl:1
	v_mov_b32_dpp v173, v25 row_shr:1 row_mask:0xf bank_mask:0xf
	v_mov_b32_dpp v177, v17 row_shr:1 row_mask:0xf bank_mask:0xf
	v_mov_b32_dpp v179, v9 row_shr:1 row_mask:0xf bank_mask:0xf
	v_mov_b32_dpp v181, v29 row_shl:1 row_mask:0xf bank_mask:0xf
	v_mov_b32_dpp v183, v25 row_shl:1 row_mask:0xf bank_mask:0xf
	v_mov_b32_dpp v185, v17 row_shl:1 row_mask:0xf bank_mask:0xf
	v_mov_b32_dpp v187, v9 row_shl:1 row_mask:0xf bank_mask:0xf bound_ctrl:1
	v_pk_fma_f32 v[170:171], v[170:171], v[140:141], v[124:125]
	v_pk_fma_f32 v[172:173], v[172:173], v[140:141], v[124:125]
	v_pk_fma_f32 v[176:177], v[176:177], v[140:141], v[124:125]
	v_pk_fma_f32 v[178:179], v[178:179], v[140:141], v[124:125]
	v_pk_fma_f32 v[170:171], v[28:29], v[116:117], v[170:171]
	v_pk_fma_f32 v[172:173], v[24:25], v[116:117], v[172:173]
	v_pk_fma_f32 v[176:177], v[16:17], v[116:117], v[176:177]
	v_pk_fma_f32 v[178:179], v[8:9], v[116:117], v[178:179]
	v_pk_fma_f32 v[170:171], v[180:181], v[120:121], v[170:171]
	v_pk_fma_f32 v[172:173], v[182:183], v[120:121], v[172:173]
	v_pk_fma_f32 v[176:177], v[184:185], v[120:121], v[176:177]
	v_pk_fma_f32 v[178:179], v[186:187], v[120:121], v[178:179]
	v_pk_mul_f32 v[180:181], v[170:171], v[188:189]
	v_pk_mul_f32 v[182:183], v[172:173], v[188:189]
	v_pk_mul_f32 v[184:185], v[176:177], v[188:189]
	v_pk_mul_f32 v[186:187], v[178:179], v[188:189]
	v_exp_f32_e32 v180, v180
	v_exp_f32_e32 v181, v181
	v_exp_f32_e32 v182, v182
	v_exp_f32_e32 v183, v183
	v_exp_f32_e32 v184, v184
	v_exp_f32_e32 v185, v185
	v_exp_f32_e32 v186, v186
	v_exp_f32_e32 v187, v187
	s_nop 0
	v_pk_add_f32 v[180:181], v[180:181], 1.0 op_sel_hi:[1,0]
	v_pk_add_f32 v[182:183], v[182:183], 1.0 op_sel_hi:[1,0]
	v_pk_add_f32 v[184:185], v[184:185], 1.0 op_sel_hi:[1,0]
	v_pk_add_f32 v[186:187], v[186:187], 1.0 op_sel_hi:[1,0]
	v_rcp_f32_e32 v180, v180
	v_rcp_f32_e32 v181, v181
	v_rcp_f32_e32 v182, v182
	v_rcp_f32_e32 v183, v183
	v_rcp_f32_e32 v184, v184
	v_rcp_f32_e32 v185, v185
	v_rcp_f32_e32 v186, v186
	v_rcp_f32_e32 v187, v187
	s_nop 0
	v_pk_mul_f32 v[28:29], v[170:171], v[180:181]
	v_pk_mul_f32 v[24:25], v[172:173], v[182:183]
	v_pk_mul_f32 v[16:17], v[176:177], v[184:185]
	v_pk_mul_f32 v[8:9], v[178:179], v[186:187]
	v_pk_mul_f32 v[28:29], v[28:29], v[20:21]
	v_pk_mul_f32 v[24:25], v[24:25], v[12:13]
	v_pk_mul_f32 v[16:17], v[16:17], v[4:5]
	v_pk_mul_f32 v[8:9], v[8:9], v[0:1]
	v_mov_b32_dpp v172, v30 row_ror:1 row_mask:0xf bank_mask:0xf
	v_mov_b32_dpp v176, v26 row_ror:1 row_mask:0xf bank_mask:0xf
	v_mov_b32_dpp v178, v18 row_ror:1 row_mask:0xf bank_mask:0xf
	v_mov_b32_dpp v180, v26 row_ror:15 row_mask:0xf bank_mask:0xf
	v_mov_b32_dpp v182, v18 row_ror:15 row_mask:0xf bank_mask:0xf
	v_mov_b32_dpp v184, v10 row_ror:15 row_mask:0xf bank_mask:0xf
	v_mov_b32_dpp v173, v31 row_ror:1 row_mask:0xf bank_mask:0xf
	v_mov_b32_dpp v177, v27 row_ror:1 row_mask:0xf bank_mask:0xf
	v_mov_b32_dpp v179, v19 row_ror:1 row_mask:0xf bank_mask:0xf
	v_mov_b32_dpp v181, v27 row_ror:15 row_mask:0xf bank_mask:0xf
	v_mov_b32_dpp v183, v19 row_ror:15 row_mask:0xf bank_mask:0xf
	v_mov_b32_dpp v185, v11 row_ror:15 row_mask:0xf bank_mask:0xf
	v_mov_b32_dpp v170, v30 row_shr:1 row_mask:0xf bank_mask:0xf bound_ctrl:1
	v_mov_b32_dpp v172, v26 row_shr:1 row_mask:0xf bank_mask:0xf
	v_mov_b32_dpp v176, v18 row_shr:1 row_mask:0xf bank_mask:0xf
	v_mov_b32_dpp v178, v10 row_shr:1 row_mask:0xf bank_mask:0xf
	v_mov_b32_dpp v180, v30 row_shl:1 row_mask:0xf bank_mask:0xf
	v_mov_b32_dpp v182, v26 row_shl:1 row_mask:0xf bank_mask:0xf
	v_mov_b32_dpp v184, v18 row_shl:1 row_mask:0xf bank_mask:0xf
	v_mov_b32_dpp v186, v10 row_shl:1 row_mask:0xf bank_mask:0xf bound_ctrl:1
	v_mov_b32_dpp v171, v31 row_shr:1 row_mask:0xf bank_mask:0xf bound_ctrl:1
	v_mov_b32_dpp v173, v27 row_shr:1 row_mask:0xf bank_mask:0xf
	v_mov_b32_dpp v177, v19 row_shr:1 row_mask:0xf bank_mask:0xf
	v_mov_b32_dpp v179, v11 row_shr:1 row_mask:0xf bank_mask:0xf
	v_mov_b32_dpp v181, v31 row_shl:1 row_mask:0xf bank_mask:0xf
	v_mov_b32_dpp v183, v27 row_shl:1 row_mask:0xf bank_mask:0xf
	v_mov_b32_dpp v185, v19 row_shl:1 row_mask:0xf bank_mask:0xf
	v_mov_b32_dpp v187, v11 row_shl:1 row_mask:0xf bank_mask:0xf bound_ctrl:1
	v_pk_fma_f32 v[170:171], v[170:171], v[142:143], v[126:127]
	v_pk_fma_f32 v[172:173], v[172:173], v[142:143], v[126:127]
	v_pk_fma_f32 v[176:177], v[176:177], v[142:143], v[126:127]
	v_pk_fma_f32 v[178:179], v[178:179], v[142:143], v[126:127]
	v_pk_fma_f32 v[170:171], v[30:31], v[118:119], v[170:171]
	v_pk_fma_f32 v[172:173], v[26:27], v[118:119], v[172:173]
	v_pk_fma_f32 v[176:177], v[18:19], v[118:119], v[176:177]
	v_pk_fma_f32 v[178:179], v[10:11], v[118:119], v[178:179]
	v_pk_fma_f32 v[170:171], v[180:181], v[122:123], v[170:171]
	v_pk_fma_f32 v[172:173], v[182:183], v[122:123], v[172:173]
	v_pk_fma_f32 v[176:177], v[184:185], v[122:123], v[176:177]
	v_pk_fma_f32 v[178:179], v[186:187], v[122:123], v[178:179]
	v_pk_mul_f32 v[180:181], v[170:171], v[188:189]
	v_pk_mul_f32 v[182:183], v[172:173], v[188:189]
	v_pk_mul_f32 v[184:185], v[176:177], v[188:189]
	v_pk_mul_f32 v[186:187], v[178:179], v[188:189]
	v_exp_f32_e32 v180, v180
	v_exp_f32_e32 v181, v181
	v_exp_f32_e32 v182, v182
	v_exp_f32_e32 v183, v183
	v_exp_f32_e32 v184, v184
	v_exp_f32_e32 v185, v185
	v_exp_f32_e32 v186, v186
	v_exp_f32_e32 v187, v187
	s_nop 0
	v_pk_add_f32 v[180:181], v[180:181], 1.0 op_sel_hi:[1,0]
	v_pk_add_f32 v[182:183], v[182:183], 1.0 op_sel_hi:[1,0]
	v_pk_add_f32 v[184:185], v[184:185], 1.0 op_sel_hi:[1,0]
	v_pk_add_f32 v[186:187], v[186:187], 1.0 op_sel_hi:[1,0]
	v_rcp_f32_e32 v180, v180
	v_rcp_f32_e32 v181, v181
	v_rcp_f32_e32 v182, v182
	v_rcp_f32_e32 v183, v183
	v_rcp_f32_e32 v184, v184
	v_rcp_f32_e32 v185, v185
	v_rcp_f32_e32 v186, v186
	v_rcp_f32_e32 v187, v187
	s_nop 0
	v_pk_mul_f32 v[30:31], v[170:171], v[180:181]
	v_pk_mul_f32 v[26:27], v[172:173], v[182:183]
	v_pk_mul_f32 v[18:19], v[176:177], v[184:185]
	v_pk_mul_f32 v[10:11], v[178:179], v[186:187]
	v_pk_mul_f32 v[30:31], v[30:31], v[22:23]
	v_pk_mul_f32 v[26:27], v[26:27], v[14:15]
	v_pk_mul_f32 v[18:19], v[18:19], v[6:7]
	v_pk_mul_f32 v[10:11], v[10:11], v[2:3]
	v_cvt_pk_bf16_f32 v52, v60, v61
	v_cvt_pk_bf16_f32 v53, v62, v63
	v_cvt_pk_bf16_f32 v54, v28, v29
	v_cvt_pk_bf16_f32 v55, v30, v31
	v_add_u32_e32 v195, 0xb0000, v194
	buffer_store_dwordx4 v[52:55], v195, s[24:27], 0 offen sc1
	v_cvt_pk_bf16_f32 v44, v56, v57
	v_cvt_pk_bf16_f32 v45, v58, v59
	v_cvt_pk_bf16_f32 v46, v24, v25
	v_cvt_pk_bf16_f32 v47, v26, v27
	v_add_u32_e32 v195, 0xc6000, v194
	buffer_store_dwordx4 v[44:47], v195, s[24:27], 0 offen sc1
	v_cvt_pk_bf16_f32 v36, v48, v49
	v_cvt_pk_bf16_f32 v37, v50, v51
	v_cvt_pk_bf16_f32 v38, v16, v17
	v_cvt_pk_bf16_f32 v39, v18, v19
	v_add_u32_e32 v195, 0xdc000, v194
	buffer_store_dwordx4 v[36:39], v195, s[24:27], 0 offen sc1
	v_cvt_pk_bf16_f32 v32, v40, v41
	v_cvt_pk_bf16_f32 v33, v42, v43
	v_cvt_pk_bf16_f32 v34, v8, v9
	v_cvt_pk_bf16_f32 v35, v10, v11
	v_add_u32_e32 v195, 0xf2000, v194
	buffer_store_dwordx4 v[32:35], v195, s[24:27], 0 offen sc1
	s_mov_b64 s[24:25], -1
	s_cbranch_vccnz .LBB0_775
	s_andn2_b64 vcc, exec, s[8:9]
	s_cbranch_vccnz .LBB0_774
	s_barrier
	s_branch .LBB0_774
